# overlap across segments: leading half's epilogue alignment barrier moved after the address block and g*u products (SwiGLU epilogues)
# baseline (speedup 1.0000x reference)
; #define PG8_BAR __builtin_amdgcn_s_barrier()
; template <class Epi, class Sched, bool ALIGN_EPI = false, bool SP2 = false>
; __device__ __forceinline__ void gemm_phase(PG8_LAS unsigned char* lds, const Gemm g, const Sched& S, const Epi& E) {
;     ...
;         if constexpr (ALIGN_EPI) { if (wr == 0) PG8_BAR; }
;     DI void operator()(const f32x4 (&acc)[2][2][4][2], const pg8::Unit& u, int wr, int wc, int fr, int fq) const {
;         const int row0 = u.pm * 256 + wr * 64 + fr, col0 = u.pn * 128 + wc * 32 + 8 * fq;
;         float rs[2][4]; row_rstd(ssq, row0, fq, rs);
; #pragma unroll
;         for (int ai = 0; ai < 2; ++ai)
; #pragma unroll
;             for (int m = 0; m < 4; ++m) {
;                 typedef float f32x2 __attribute__((ext_vector_type(2)));
;                 const float r = rs[ai][m]; const float r2s = r * r, rls = r * -1.44269504f; const f32x2 r2 = {r2s, r2s}, rl = {rls, rls};
;                 unsigned hw[4];
; #pragma unroll
;                 for (int q = 0; q < 4; ++q) {
;                     const f32x4 gq = acc[ai][0][m][q >> 1], uq = acc[ai][1][m][q >> 1];
;                     const f32x2 g2 = {gq[2 * (q & 1)], gq[2 * (q & 1) + 1]}, u2 = {uq[2 * (q & 1)], uq[2 * (q & 1) + 1]};
;                     const f32x2 t = g2 * rl; f32x2 e; e.x = __builtin_amdgcn_exp2f(t.x); e.y = __builtin_amdgcn_exp2f(t.y);
;                     const f32x2 d = e + 1.0f; f32x2 rc; rc.x = __builtin_amdgcn_rcpf(d.x); rc.y = __builtin_amdgcn_rcpf(d.y);
;                     const f32x2 hv = ((g2 * u2) * r2) * rc;
.Lrc_skip_0:
.LBB0_169:
	v_and_b32_e32 v131, 64, v194
	v_xor_b32_e32 v130, 16, v194
	v_add_u32_e32 v131, 64, v131
	v_cmp_lt_i32_e32 vcc, v130, v131
	v_lshl_add_u32 v160, s58, 8, v182
	v_ashrrev_i32_e32 v161, 31, v160
	v_cndmask_b32_e32 v130, v194, v130, vcc
	v_lshlrev_b32_e32 v186, 2, v130
	v_xor_b32_e32 v130, 32, v194
	v_cmp_lt_i32_e32 vcc, v130, v131
	v_or_b32_e32 v158, 16, v160
	v_ashrrev_i32_e32 v159, 31, v158
	v_cndmask_b32_e32 v130, v194, v130, vcc
	v_lshlrev_b32_e32 v163, 2, v130
	v_lshlrev_b64 v[130:131], 6, v[160:161]
	v_lshl_add_u64 v[130:131], v[140:141], 0, v[130:131]
	v_mov_b64_e32 v[178:179], s[16:17]
	v_or_b32_e32 v156, 32, v160
	v_ashrrev_i32_e32 v157, 31, v156
	v_or_b32_e32 v154, 48, v160
	v_ashrrev_i32_e32 v155, 31, v154
	v_add_u32_e32 v152, 0x80, v160
	v_ashrrev_i32_e32 v153, 31, v152
	v_add_u32_e32 v150, 0x90, v160
	v_ashrrev_i32_e32 v151, 31, v150
	v_pk_mul_f32 v[122:123], v[126:127], v[122:123]
	v_pk_mul_f32 v[124:125], v[128:129], v[124:125]
	v_pk_mul_f32 v[114:115], v[118:119], v[114:115]
	v_pk_mul_f32 v[116:117], v[120:121], v[116:117]
	v_lshl_or_b32 v162, s57, 7, v184
	v_pk_mul_f32 v[106:107], v[110:111], v[106:107]
	v_pk_mul_f32 v[108:109], v[112:113], v[108:109]
	v_pk_mul_f32 v[98:99], v[102:103], v[98:99]
	v_pk_mul_f32 v[100:101], v[104:105], v[100:101]
	v_pk_mul_f32 v[90:91], v[94:95], v[90:91]
	v_pk_mul_f32 v[92:93], v[96:97], v[92:93]
	v_pk_mul_f32 v[82:83], v[86:87], v[82:83]
	v_pk_mul_f32 v[84:85], v[88:89], v[84:85]
	v_pk_mul_f32 v[74:75], v[78:79], v[74:75]
	v_pk_mul_f32 v[76:77], v[80:81], v[76:77]
	v_pk_mul_f32 v[66:67], v[70:71], v[66:67]
	v_pk_mul_f32 v[68:69], v[72:73], v[68:69]
	v_pk_mul_f32 v[58:59], v[62:63], v[58:59]
	v_pk_mul_f32 v[60:61], v[64:65], v[60:61]
	v_pk_mul_f32 v[50:51], v[54:55], v[50:51]
	v_pk_mul_f32 v[52:53], v[56:57], v[52:53]
	v_pk_mul_f32 v[42:43], v[46:47], v[42:43]
	v_pk_mul_f32 v[44:45], v[48:49], v[44:45]
	v_pk_mul_f32 v[34:35], v[38:39], v[34:35]
	v_pk_mul_f32 v[36:37], v[40:41], v[36:37]
	v_pk_mul_f32 v[26:27], v[30:31], v[26:27]
	v_pk_mul_f32 v[28:29], v[32:33], v[28:29]
	v_pk_mul_f32 v[18:19], v[22:23], v[18:19]
	v_pk_mul_f32 v[20:21], v[24:25], v[20:21]
	v_pk_mul_f32 v[10:11], v[14:15], v[10:11]
	v_pk_mul_f32 v[12:13], v[16:17], v[12:13]
	v_pk_mul_f32 v[2:3], v[6:7], v[2:3]
	v_pk_mul_f32 v[4:5], v[8:9], v[4:5]
	s_and_b64 vcc, exec, s[42:43]
	s_cbranch_vccz .Lab_0
	s_barrier
; DI void row_rstd(const float* ssq, int row0, int fq, float (&rs)[2][4]) {
; #pragma unroll
;     for (int ai = 0; ai < 2; ++ai)
; #pragma unroll
;         for (int m = 0; m < 4; ++m) {
;             const f32x4 v = *(const f32x4*)(ssq + (size_t)(row0 + ai * 128 + m * 16) * 16 + 4 * fq);
;             float s = (v[0] + v[1]) + (v[2] + v[3]);
;             s += __shfl_xor(s, 16); s += __shfl_xor(s, 32);
;             rs[ai][m] = rsqrtf(s * (1.0f / DM) + EPS);
;         }
; }
.Lab_0:
	s_cmp_eq_u32 s58, s98
	s_cbranch_scc1 .Lrc_hit_0
	s_waitcnt vmcnt(7)
	v_mov_b32_e32 v130, v202
	v_mov_b32_e32 v131, v203
	v_mov_b32_e32 v132, v204
	v_mov_b32_e32 v133, v205
	v_mov_b32_e32 v146, v131
	v_mov_b32_e32 v147, v132
	v_mov_b32_e32 v131, v133
	v_pk_add_f32 v[146:147], v[146:147], v[130:131]
	v_lshlrev_b64 v[130:131], 6, v[158:159]
	v_lshl_add_u64 v[130:131], v[140:141], 0, v[130:131]
	s_waitcnt vmcnt(6)
	v_mov_b32_e32 v130, v206
	v_mov_b32_e32 v131, v207
	v_mov_b32_e32 v132, v208
	v_mov_b32_e32 v133, v209
	v_mov_b32_e32 v148, v131
	v_mov_b32_e32 v149, v132
	v_mov_b32_e32 v131, v133
	v_pk_add_f32 v[130:131], v[148:149], v[130:131]
	v_mov_b32_e32 v133, v146
	v_mov_b32_e32 v132, v130
	v_mov_b32_e32 v146, v131
	v_pk_add_f32 v[130:131], v[132:133], v[146:147]
	ds_bpermute_b32 v133, v186, v131
	ds_bpermute_b32 v132, v186, v130
	s_waitcnt lgkmcnt(0)
	v_pk_add_f32 v[130:131], v[130:131], v[132:133]
	ds_bpermute_b32 v133, v163, v131
	ds_bpermute_b32 v132, v163, v130
	s_waitcnt lgkmcnt(0)
	v_pk_add_f32 v[130:131], v[130:131], v[132:133]
	s_nop 0
	v_pk_fma_f32 v[130:131], v[130:131], s[34:35], v[178:179] op_sel_hi:[1,0,0]
	s_nop 0
	v_mul_f32_e32 v132, 0x4b800000, v131
	v_cmp_gt_f32_e64 s[2:3], s25, v131
	v_cmp_gt_f32_e32 vcc, s25, v130
	s_nop 0
	v_cndmask_b32_e64 v131, v131, v132, s[2:3]
	v_rsq_f32_e32 v131, v131
	s_nop 0
	v_mul_f32_e32 v132, 0x45800000, v131
	v_cndmask_b32_e64 v161, v131, v132, s[2:3]
	v_mul_f32_e32 v131, 0x4b800000, v130
	v_cndmask_b32_e32 v130, v130, v131, vcc
	v_rsq_f32_e32 v130, v130
	s_nop 0
	v_mul_f32_e32 v131, 0x45800000, v130
	v_cndmask_b32_e32 v159, v130, v131, vcc
	v_lshlrev_b64 v[130:131], 6, v[156:157]
	v_lshl_add_u64 v[130:131], v[140:141], 0, v[130:131]
	s_waitcnt vmcnt(5)
	v_mov_b32_e32 v130, v210
	v_mov_b32_e32 v131, v211
	v_mov_b32_e32 v132, v212
	v_mov_b32_e32 v133, v213
	v_mov_b32_e32 v146, v131
	v_mov_b32_e32 v147, v132
	v_mov_b32_e32 v131, v133
	v_pk_add_f32 v[146:147], v[146:147], v[130:131]
	v_lshlrev_b64 v[130:131], 6, v[154:155]
	v_lshl_add_u64 v[130:131], v[140:141], 0, v[130:131]
	s_waitcnt vmcnt(4)
	v_mov_b32_e32 v130, v214
	v_mov_b32_e32 v131, v215
	v_mov_b32_e32 v132, v216
	v_mov_b32_e32 v133, v217
	v_mov_b32_e32 v148, v131
	v_mov_b32_e32 v149, v132
	v_mov_b32_e32 v131, v133
	v_pk_add_f32 v[130:131], v[148:149], v[130:131]
	v_mov_b32_e32 v133, v146
	v_mov_b32_e32 v132, v130
	v_mov_b32_e32 v146, v131
	v_pk_add_f32 v[130:131], v[132:133], v[146:147]
	ds_bpermute_b32 v133, v186, v131
	ds_bpermute_b32 v132, v186, v130
	s_waitcnt lgkmcnt(0)
	v_pk_add_f32 v[130:131], v[130:131], v[132:133]
	ds_bpermute_b32 v133, v163, v131
	ds_bpermute_b32 v132, v163, v130
	s_waitcnt lgkmcnt(0)
	v_pk_add_f32 v[130:131], v[130:131], v[132:133]
	s_nop 0
	v_pk_fma_f32 v[130:131], v[130:131], s[34:35], v[178:179] op_sel_hi:[1,0,0]
	s_nop 0
	v_mul_f32_e32 v132, 0x4b800000, v131
	v_cmp_gt_f32_e64 s[2:3], s25, v131
	v_cmp_gt_f32_e32 vcc, s25, v130
	s_nop 0
	v_cndmask_b32_e64 v131, v131, v132, s[2:3]
	v_rsq_f32_e32 v131, v131
	s_nop 0
	v_mul_f32_e32 v132, 0x45800000, v131
	v_cndmask_b32_e64 v157, v131, v132, s[2:3]
	v_mul_f32_e32 v131, 0x4b800000, v130
	v_cndmask_b32_e32 v130, v130, v131, vcc
	v_rsq_f32_e32 v130, v130
	s_nop 0
	v_mul_f32_e32 v131, 0x45800000, v130
	v_cndmask_b32_e32 v155, v130, v131, vcc
	v_lshlrev_b64 v[130:131], 6, v[152:153]
	v_lshl_add_u64 v[130:131], v[140:141], 0, v[130:131]
	s_waitcnt vmcnt(3)
	v_mov_b32_e32 v130, v218
	v_mov_b32_e32 v131, v219
	v_mov_b32_e32 v132, v220
	v_mov_b32_e32 v133, v221
	v_mov_b32_e32 v146, v131
	v_mov_b32_e32 v147, v132
	v_mov_b32_e32 v131, v133
	v_pk_add_f32 v[146:147], v[146:147], v[130:131]
	v_lshlrev_b64 v[130:131], 6, v[150:151]
	v_lshl_add_u64 v[130:131], v[140:141], 0, v[130:131]
	s_waitcnt vmcnt(2)
	v_mov_b32_e32 v130, v222
	v_mov_b32_e32 v131, v223
	v_mov_b32_e32 v132, v224
	v_mov_b32_e32 v133, v225
	v_mov_b32_e32 v148, v131
	v_mov_b32_e32 v149, v132
	v_mov_b32_e32 v131, v133
	v_pk_add_f32 v[130:131], v[148:149], v[130:131]
	v_mov_b32_e32 v133, v146
	v_mov_b32_e32 v132, v130
	v_mov_b32_e32 v146, v131
	v_pk_add_f32 v[130:131], v[132:133], v[146:147]
	ds_bpermute_b32 v133, v186, v131
	ds_bpermute_b32 v132, v186, v130
	v_add_u32_e32 v148, 0xa0, v160
	v_ashrrev_i32_e32 v149, 31, v148
	s_waitcnt lgkmcnt(0)
	v_pk_add_f32 v[130:131], v[130:131], v[132:133]
	ds_bpermute_b32 v133, v163, v131
	ds_bpermute_b32 v132, v163, v130
	s_waitcnt lgkmcnt(0)
	v_pk_add_f32 v[130:131], v[130:131], v[132:133]
	s_nop 0
	v_pk_fma_f32 v[130:131], v[130:131], s[34:35], v[178:179] op_sel_hi:[1,0,0]
	s_nop 0
	v_mul_f32_e32 v132, 0x4b800000, v131
	v_cmp_gt_f32_e64 s[2:3], s25, v131
	v_cmp_gt_f32_e32 vcc, s25, v130
	s_nop 0
	v_cndmask_b32_e64 v131, v131, v132, s[2:3]
	v_rsq_f32_e32 v131, v131
	s_nop 0
	v_mul_f32_e32 v132, 0x45800000, v131
	v_cndmask_b32_e64 v153, v131, v132, s[2:3]
	v_mul_f32_e32 v131, 0x4b800000, v130
	v_cndmask_b32_e32 v130, v130, v131, vcc
	v_rsq_f32_e32 v130, v130
	s_nop 0
	v_mul_f32_e32 v131, 0x45800000, v130
	v_cndmask_b32_e32 v151, v130, v131, vcc
	v_lshlrev_b64 v[130:131], 6, v[148:149]
	v_lshl_add_u64 v[130:131], v[140:141], 0, v[130:131]
	v_accvgpr_write_b32 a0, v161
	v_accvgpr_write_b32 a1, v159
	v_accvgpr_write_b32 a2, v157
	v_accvgpr_write_b32 a3, v155
	v_accvgpr_write_b32 a4, v153
	v_accvgpr_write_b32 a5, v151
	s_waitcnt vmcnt(1)
	v_mov_b32_e32 v130, v226
	v_mov_b32_e32 v131, v227
	v_mov_b32_e32 v132, v228
	v_mov_b32_e32 v133, v229
	v_mov_b32_e32 v146, v131
	v_mov_b32_e32 v147, v132
	v_mov_b32_e32 v131, v133
	v_pk_add_f32 v[180:181], v[146:147], v[130:131]
	v_add_u32_e32 v146, 0xb0, v160
	v_ashrrev_i32_e32 v147, 31, v146
	v_lshlrev_b64 v[130:131], 6, v[146:147]
	v_lshl_add_u64 v[130:131], v[140:141], 0, v[130:131]
	s_waitcnt vmcnt(0)
	v_mov_b32_e32 v130, v230
	v_mov_b32_e32 v131, v231
	v_mov_b32_e32 v132, v232
	v_mov_b32_e32 v133, v233
	v_mov_b32_e32 v188, v131
	v_mov_b32_e32 v189, v132
	v_mov_b32_e32 v131, v133
	v_pk_add_f32 v[130:131], v[188:189], v[130:131]
	v_mov_b32_e32 v133, v180
	v_mov_b32_e32 v132, v130
	v_mov_b32_e32 v180, v131
	v_pk_add_f32 v[130:131], v[132:133], v[180:181]
	ds_bpermute_b32 v133, v186, v131
	ds_bpermute_b32 v132, v186, v130
	s_waitcnt lgkmcnt(0)
	v_pk_add_f32 v[130:131], v[130:131], v[132:133]
	ds_bpermute_b32 v133, v163, v131
	ds_bpermute_b32 v132, v163, v130
	v_ashrrev_i32_e32 v163, 31, v162
	s_waitcnt lgkmcnt(0)
	v_pk_add_f32 v[130:131], v[130:131], v[132:133]
	s_nop 0
	v_pk_fma_f32 v[130:131], v[130:131], s[34:35], v[178:179] op_sel_hi:[1,0,0]
	v_mul_f32_e32 v132, 0x4b800000, v131
	v_cmp_gt_f32_e64 s[2:3], s25, v131
	s_nop 1
	v_cndmask_b32_e64 v131, v131, v132, s[2:3]
	v_rsq_f32_e32 v131, v131
	s_nop 0
	v_cmp_gt_f32_e32 vcc, s25, v130
	v_mul_f32_e32 v132, 0x45800000, v131
	v_cndmask_b32_e64 v131, v131, v132, s[2:3]
	v_mul_f32_e32 v132, 0x4b800000, v130
	v_cndmask_b32_e32 v130, v130, v132, vcc
	v_rsq_f32_e32 v130, v130
	s_nop 0
	v_mul_f32_e32 v132, 0x45800000, v130
	v_cndmask_b32_e32 v130, v130, v132, vcc
	v_accvgpr_write_b32 a6, v131
	v_accvgpr_write_b32 a7, v130
	s_mov_b32 s98, s58
	s_branch .Lrc_done_0

;     DI void operator()(const f32x4 (&acc)[2][2][4][2], const pg8::Unit& u, int wr, int wc, int fr, int fq) const {
;         const int row0 = u.pm * 256 + wr * 64 + fr, col0 = u.pn * 128 + wc * 32 + 8 * fq;
;         float rs[2][4]; row_rstd(ssq, row0, fq, rs);
; #pragma unroll
;         for (int ai = 0; ai < 2; ++ai)
; #pragma unroll
;             for (int m = 0; m < 4; ++m) {
;                 typedef float f32x2 __attribute__((ext_vector_type(2)));
;                 const float r = rs[ai][m]; const float r2s = r * r, rls = r * -1.44269504f; const f32x2 r2 = {r2s, r2s}, rl = {rls, rls};
;                 unsigned hw[4];
; #pragma unroll
;                 for (int q = 0; q < 4; ++q) {
;                     const f32x4 gq = acc[ai][0][m][q >> 1], uq = acc[ai][1][m][q >> 1];
;                     const f32x2 g2 = {gq[2 * (q & 1)], gq[2 * (q & 1) + 1]}, u2 = {uq[2 * (q & 1)], uq[2 * (q & 1) + 1]};
;                     const f32x2 t = g2 * rl; f32x2 e; e.x = __builtin_amdgcn_exp2f(t.x); e.y = __builtin_amdgcn_exp2f(t.y);
;                     const f32x2 d = e + 1.0f; f32x2 rc; rc.x = __builtin_amdgcn_rcpf(d.x); rc.y = __builtin_amdgcn_rcpf(d.y);
;                     const f32x2 hv = ((g2 * u2) * r2) * rc;
.Lrc_skip_1:
.LBB0_1125:
	v_and_b32_e32 v131, 64, v194
	v_xor_b32_e32 v130, 16, v194
	v_add_u32_e32 v131, 64, v131
	v_cmp_lt_i32_e32 vcc, v130, v131
	v_lshl_add_u32 v160, s58, 8, v182
	v_ashrrev_i32_e32 v161, 31, v160
	v_cndmask_b32_e32 v130, v194, v130, vcc
	v_lshlrev_b32_e32 v186, 2, v130
	v_xor_b32_e32 v130, 32, v194
	v_cmp_lt_i32_e32 vcc, v130, v131
	v_or_b32_e32 v158, 16, v160
	v_ashrrev_i32_e32 v159, 31, v158
	v_cndmask_b32_e32 v130, v194, v130, vcc
	v_lshlrev_b32_e32 v163, 2, v130
	v_lshlrev_b64 v[130:131], 6, v[160:161]
	v_lshl_add_u64 v[130:131], v[140:141], 0, v[130:131]
	v_mov_b64_e32 v[178:179], s[16:17]
	v_or_b32_e32 v156, 32, v160
	v_ashrrev_i32_e32 v157, 31, v156
	v_or_b32_e32 v154, 48, v160
	v_ashrrev_i32_e32 v155, 31, v154
	v_add_u32_e32 v152, 0x80, v160
	v_ashrrev_i32_e32 v153, 31, v152
	v_add_u32_e32 v150, 0x90, v160
	v_ashrrev_i32_e32 v151, 31, v150
	v_pk_mul_f32 v[122:123], v[126:127], v[122:123]
	v_pk_mul_f32 v[124:125], v[128:129], v[124:125]
	v_pk_mul_f32 v[114:115], v[118:119], v[114:115]
	v_pk_mul_f32 v[116:117], v[120:121], v[116:117]
	v_lshl_or_b32 v162, s57, 7, v184
	v_pk_mul_f32 v[106:107], v[110:111], v[106:107]
	v_pk_mul_f32 v[108:109], v[112:113], v[108:109]
	v_pk_mul_f32 v[98:99], v[102:103], v[98:99]
	v_pk_mul_f32 v[100:101], v[104:105], v[100:101]
	v_pk_mul_f32 v[90:91], v[94:95], v[90:91]
	v_pk_mul_f32 v[92:93], v[96:97], v[92:93]
	v_pk_mul_f32 v[82:83], v[86:87], v[82:83]
	v_pk_mul_f32 v[84:85], v[88:89], v[84:85]
	v_pk_mul_f32 v[74:75], v[78:79], v[74:75]
	v_pk_mul_f32 v[76:77], v[80:81], v[76:77]
	v_pk_mul_f32 v[66:67], v[70:71], v[66:67]
	v_pk_mul_f32 v[68:69], v[72:73], v[68:69]
	v_pk_mul_f32 v[58:59], v[62:63], v[58:59]
	v_pk_mul_f32 v[60:61], v[64:65], v[60:61]
	v_pk_mul_f32 v[50:51], v[54:55], v[50:51]
	v_pk_mul_f32 v[52:53], v[56:57], v[52:53]
	v_pk_mul_f32 v[42:43], v[46:47], v[42:43]
	v_pk_mul_f32 v[44:45], v[48:49], v[44:45]
	v_pk_mul_f32 v[34:35], v[38:39], v[34:35]
	v_pk_mul_f32 v[36:37], v[40:41], v[36:37]
	v_pk_mul_f32 v[26:27], v[30:31], v[26:27]
	v_pk_mul_f32 v[28:29], v[32:33], v[28:29]
	v_pk_mul_f32 v[18:19], v[22:23], v[18:19]
	v_pk_mul_f32 v[20:21], v[24:25], v[20:21]
	v_pk_mul_f32 v[10:11], v[14:15], v[10:11]
	v_pk_mul_f32 v[12:13], v[16:17], v[12:13]
	v_pk_mul_f32 v[2:3], v[6:7], v[2:3]
	v_pk_mul_f32 v[4:5], v[8:9], v[4:5]
	s_and_b64 vcc, exec, s[44:45]
	s_cbranch_vccz .Lab_1
	s_barrier
